# opt17: final1 + all 14 GEMM prologue LDS-DMA loads issued before the first wait (one exposed round trip less per GEMM phase)
# baseline (speedup 1.0000x reference)
; #define PG8_STAGE(bufoff, gbase, voff) do { _Pragma("unroll") for (int _i = 0; _i < 2; ++_i) \
;         __builtin_amdgcn_global_load_lds((const unsigned*)((const char*)(gbase) + (voff)[_i]), (PG8_LAS unsigned*)(lds + (bufoff) + ldsw + _i * 8192), 16, 0, 0); } while (0)
; #define PG8_WAIT_V(n) asm volatile("s_waitcnt vmcnt(" #n ")" ::: "memory")
; #define PG8_BAR __builtin_amdgcn_s_barrier()
; template <class Epi>
; __device__ __forceinline__ void gemm_phase(PG8_LAS unsigned char* lds, const Gemm g, const StaticOrder& S_, const Epi& E) {
;     ...
;     PG8_STAGE(PG8_SB(0, 0), cB, voffB); PG8_STAGE(PG8_SB(0, 1), cB + hstepB, voffB); PG8_STAGE(PG8_SA(0, 0), cA, voffA); PG8_STAGE(PG8_SA(0, 1), cA + hstepA, voffA);
;     if (wr == 1) PG8_BAR;
;     PG8_WAIT_V(2); PG8_BAR;
;     PG8_STAGE(PG8_SB(1, 0), cB + kstep, voffB); PG8_STAGE(PG8_SA(1, 0), cA + kstep, voffA); PG8_STAGE(PG8_SB(1, 1), cB + hstepB + kstep, voffB);
;     PG8_WAIT_V(6); PG8_BAR;
.LBB0_177:
	s_add_u32 s22, s4, 0x8800000
	s_addc_u32 s23, s5, 0
	s_add_u32 s24, s4, 0x16800000
	s_addc_u32 s25, s5, 0
	s_add_u32 s26, s4, 0x19000000
	s_addc_u32 s27, s5, 0
	s_add_u32 s28, s4, 0x1fb00000
	s_addc_u32 s29, s5, 0
	s_add_u32 s64, s4, 0x1fd00000
	s_addc_u32 s65, s5, 0
	s_and_b32 s7, s13, 3
	s_add_i32 m0, s60, 0x18000
	v_lshl_add_u64 v[8:9], v[8:9], 0, s[86:87]
	s_lshl_b32 s66, s14, 6
	s_lshl_b32 s9, s14, 13
	s_lshl_b32 s16, s7, 12
	global_load_lds_dwordx4 v[8:9], off
	v_lshl_add_u64 v[6:7], v[6:7], 0, s[86:87]
	s_add_i32 m0, s60, 0x1a000
	s_add_i32 s67, s60, 0x8000
	s_add_i32 s68, s60, 0xa000
	global_load_lds_dwordx4 v[6:7], off
	v_lshl_add_u64 v[2:3], v[2:3], 0, s[86:87]
	s_mov_b32 m0, s67
	s_add_u32 s14, s2, 0x40080
	global_load_lds_dwordx4 v[2:3], off
	v_lshl_add_u64 v[2:3], v[4:5], 0, s[86:87]
	s_mov_b32 m0, s68
	s_addc_u32 s15, s3, 0
	global_load_lds_dwordx4 v[2:3], off
	s_add_i32 m0, s60, 0x1c000
	v_lshl_add_u64 v[2:3], s[14:15], 0, v[144:145]
	global_load_lds_dwordx4 v[2:3], off
	v_lshl_add_u64 v[2:3], s[14:15], 0, v[148:149]
	s_add_i32 m0, s60, 0x1e000
	v_and_b32_e32 v173, 15, v10
	global_load_lds_dwordx4 v[2:3], off
	s_waitcnt vmcnt(8)
	s_barrier
	v_bfe_u32 v186, v10, 4, 2
	v_lshlrev_b32_e32 v0, 4, v186
	v_lshlrev_b32_e32 v4, 2, v173
	v_lshl_or_b32 v3, v173, 6, v0
	v_and_b32_e32 v5, 32, v4
	s_cmpk_lt_u32 s12, 0x100
	v_lshlrev_b32_e32 v2, 3, v186
	v_bitop3_b32 v6, v3, s9, v5 bitop3:0xde
	s_cselect_b64 s[30:31], -1, 0
	s_bfe_u32 s69, s12, 0x10006
	s_add_i32 s9, s9, 0
	s_lshl_b32 s7, s7, 11
	v_lshl_or_b32 v188, s69, 5, v2
	v_lshlrev_b32_e32 v2, 5, v186
	s_add_i32 s71, s9, s7
	v_bitop3_b32 v187, v3, s16, v5 bitop3:0xde
	v_lshl_or_b32 v189, s69, 7, v2
	s_add_i32 s71, s71, 0x20000
	v_and_b32_e32 v2, 3, v10
	v_lshlrev_b32_e32 v5, 3, v173
	s_bfe_u32 s70, s13, 0x10001
	v_lshl_add_u32 v3, v2, 1, s71
	s_lshl_b32 s72, s69, 10
	v_lshl_or_b32 v150, v186, 7, v5
	v_lshlrev_b32_e32 v5, 9, v186
	v_and_b32_e32 v4, 48, v4
	s_ashr_i32 s73, s54, 31
	s_lshl_b32 s7, s69, 6
	v_add3_u32 v192, v3, v5, v4
	v_lshlrev_b32_e32 v4, 1, v10
	s_add_u32 s4, s4, s7
	v_add_u32_e32 v2, s71, v2
	v_lshlrev_b32_e32 v3, 8, v186
	v_and_b32_e32 v4, 24, v4
	s_addc_u32 s5, s5, 0
	v_add3_u32 v193, v2, v3, v4
	v_lshl_add_u64 v[2:3], s[4:5], 0, v[0:1]
	s_mov_b64 s[4:5], 0x3d00000
	v_lshlrev_b32_e32 v0, 14, v14
	v_lshl_add_u64 v[152:153], v[2:3], 0, s[4:5]
	s_mov_b64 s[4:5], 0x4100000
	v_and_b32_e32 v0, 0xffff8000, v0
	v_lshl_add_u64 v[154:155], v[2:3], 0, s[4:5]
	v_lshl_add_u32 v0, v15, 11, v0
	v_and_b32_e32 v2, 1, v14
	v_lshl_or_b32 v0, v2, 6, v0
	v_lshl_add_u32 v156, v16, 1, v0
	v_lshlrev_b32_e32 v0, 14, v11
	v_and_b32_e32 v0, 0xffff8000, v0
	s_waitcnt vmcnt(6)
	v_lshl_add_u32 v0, v12, 11, v0
	v_and_b32_e32 v2, 1, v11
	v_lshl_or_b32 v0, v2, 6, v0
	v_lshlrev_b32_e32 v190, 16, v173
	v_lshl_add_u32 v191, v150, 1, s71
	v_mov_b32_e32 v151, v1
	v_mov_b32_e32 v157, v1
	v_lshl_add_u32 v158, v13, 1, v0
	v_mov_b32_e32 v159, v1
	s_mov_b32 s74, 0
	v_add_u32_e32 v194, 0, v6
	s_barrier
	s_branch .LBB0_180

; #define PG8_STAGE(bufoff, gbase, voff) do { _Pragma("unroll") for (int _i = 0; _i < 2; ++_i) \
;         __builtin_amdgcn_global_load_lds((const unsigned*)((const char*)(gbase) + (voff)[_i]), (PG8_LAS unsigned*)(lds + (bufoff) + ldsw + _i * 8192), 16, 0, 0); } while (0)
; #define PG8_WAIT_V(n) asm volatile("s_waitcnt vmcnt(" #n ")" ::: "memory")
; #define PG8_BAR __builtin_amdgcn_s_barrier()
; template <class Epi>
; __device__ __forceinline__ void gemm_phase(PG8_LAS unsigned char* lds, const Gemm g, const StaticOrder& S_, const Epi& E) {
;     ...
;     PG8_STAGE(PG8_SB(0, 0), cB, voffB); PG8_STAGE(PG8_SB(0, 1), cB + hstepB, voffB); PG8_STAGE(PG8_SA(0, 0), cA, voffA); PG8_STAGE(PG8_SA(0, 1), cA + hstepA, voffA);
;     if (wr == 1) PG8_BAR;
;     PG8_WAIT_V(2); PG8_BAR;
;     PG8_STAGE(PG8_SB(1, 0), cB + kstep, voffB); PG8_STAGE(PG8_SA(1, 0), cA + kstep, voffA); PG8_STAGE(PG8_SB(1, 1), cB + hstepB + kstep, voffB);
;     PG8_WAIT_V(6); PG8_BAR;
.LBB0_1158:
	v_lshrrev_b32_e32 v18, 1, v15
	v_and_b32_e32 v18, 24, v18
	s_sext_i32_i8 s39, s6
	s_add_u32 s6, s4, 0x4800000
	v_and_b32_e32 v17, 15, v15
	v_lshlrev_b32_e32 v19, 1, v18
	v_lshlrev_b32_e32 v15, 2, v15
	s_addc_u32 s7, s5, 0
	v_lshl_or_b32 v140, s12, 6, v17
	v_lshl_or_b32 v17, v17, 6, v19
	s_lshl_b32 s4, s12, 13
	v_and_b32_e32 v15, 32, v15
	v_bitop3_b32 v19, v17, s4, v15 bitop3:0xde
	s_lshl_b32 s4, s9, 5
	s_and_b32 s12, s4, 0x60
	s_add_i32 m0, s11, 0x18000
	v_lshl_add_u64 v[8:9], v[8:9], 0, s[86:87]
	s_lshl_b32 s4, s12, 7
	global_load_lds_dwordx4 v[8:9], off
	v_lshl_add_u64 v[6:7], v[6:7], 0, s[86:87]
	s_add_i32 m0, s11, 0x1a000
	s_add_i32 s36, s11, 0x8000
	s_add_i32 s37, s11, 0xa000
	v_bitop3_b32 v141, v17, s4, v15 bitop3:0xde
	global_load_lds_dwordx4 v[6:7], off
	v_lshl_add_u64 v[2:3], v[2:3], 0, s[86:87]
	s_mov_b32 m0, s36
	s_add_u32 s4, s2, 0x40080
	global_load_lds_dwordx4 v[2:3], off
	v_lshl_add_u64 v[2:3], v[4:5], 0, s[86:87]
	s_mov_b32 m0, s37
	s_addc_u32 s5, s3, 0
	global_load_lds_dwordx4 v[2:3], off
	s_add_i32 m0, s11, 0x1c000
	v_lshl_add_u64 v[2:3], s[4:5], 0, v[0:1]
	global_load_lds_dwordx4 v[2:3], off
	v_lshl_add_u64 v[2:3], s[4:5], 0, v[134:135]
	s_add_i32 m0, s11, 0x1e000
	s_cmpk_lt_u32 s8, 0x100
	global_load_lds_dwordx4 v[2:3], off
	s_waitcnt vmcnt(8)
	s_barrier
	v_lshlrev_b32_e32 v2, 14, v13
	v_and_b32_e32 v2, 0xffff8000, v2
	v_lshl_add_u32 v2, v14, 11, v2
	v_and_b32_e32 v3, 1, v13
	v_lshl_or_b32 v2, v3, 6, v2
	v_lshl_add_u32 v136, v16, 1, v2
	v_lshlrev_b32_e32 v2, 14, v10
	v_and_b32_e32 v2, 0xffff8000, v2
	s_waitcnt vmcnt(6)
	v_lshl_add_u32 v2, v11, 11, v2
	v_and_b32_e32 v3, 1, v10
	v_lshl_or_b32 v2, v3, 6, v2
	s_cselect_b64 s[8:9], -1, 0
	v_or_b32_e32 v142, s12, v18
	v_mov_b32_e32 v137, v1
	v_lshl_add_u32 v138, v12, 1, v2
	v_mov_b32_e32 v139, v1
	s_mov_b32 s38, 0
	v_add_u32_e32 v143, 0, v19
	s_barrier
	s_waitcnt vmcnt(0)
	s_branch .LBB0_1161

; #define PG8_STAGE(bufoff, gbase, voff) do { _Pragma("unroll") for (int _i = 0; _i < 2; ++_i) \
;         __builtin_amdgcn_global_load_lds((const unsigned*)((const char*)(gbase) + (voff)[_i]), (PG8_LAS unsigned*)(lds + (bufoff) + ldsw + _i * 8192), 16, 0, 0); } while (0)
; #define PG8_WAIT_V(n) asm volatile("s_waitcnt vmcnt(" #n ")" ::: "memory")
; #define PG8_BAR __builtin_amdgcn_s_barrier()
; template <class Epi>
; __device__ __forceinline__ void gemm_phase(PG8_LAS unsigned char* lds, const Gemm g, const StaticOrder& S_, const Epi& E) {
;     ...
;     PG8_STAGE(PG8_SB(0, 0), cB, voffB); PG8_STAGE(PG8_SB(0, 1), cB + hstepB, voffB); PG8_STAGE(PG8_SA(0, 0), cA, voffA); PG8_STAGE(PG8_SA(0, 1), cA + hstepA, voffA);
;     if (wr == 1) PG8_BAR;
;     PG8_WAIT_V(2); PG8_BAR;
;     PG8_STAGE(PG8_SB(1, 0), cB + kstep, voffB); PG8_STAGE(PG8_SA(1, 0), cA + kstep, voffA); PG8_STAGE(PG8_SB(1, 1), cB + hstepB + kstep, voffB);
;     PG8_WAIT_V(6); PG8_BAR;
.LBB0_1301:
	s_add_u32 s14, s8, 0x8800000
	s_addc_u32 s15, s9, 0
	s_add_u32 s16, s4, s64
	s_addc_u32 s17, s5, s63
	s_add_u32 s18, s6, s65
	s_addc_u32 s19, s7, s62
	s_add_u32 s20, s8, 0x13800000
	s_addc_u32 s21, s9, 0
	s_add_u32 s22, s8, 0x13e00000
	s_addc_u32 s23, s9, 0
	s_and_b32 s33, s24, 3
	s_add_i32 m0, s72, 0x18000
	v_lshl_add_u64 v[8:9], v[8:9], 0, s[86:87]
	s_lshl_b32 s6, s11, 13
	s_lshl_b32 s7, s33, 12
	global_load_lds_dwordx4 v[8:9], off
	v_lshl_add_u64 v[6:7], v[6:7], 0, s[86:87]
	s_add_i32 m0, s72, 0x1a000
	s_add_i32 s77, s72, 0x8000
	s_add_i32 s78, s72, 0xa000
	global_load_lds_dwordx4 v[6:7], off
	v_lshl_add_u64 v[2:3], v[2:3], 0, s[86:87]
	s_mov_b32 m0, s77
	s_add_u32 s4, s2, 0x40080
	global_load_lds_dwordx4 v[2:3], off
	v_lshl_add_u64 v[2:3], v[4:5], 0, s[86:87]
	s_mov_b32 m0, s78
	s_addc_u32 s5, s3, 0
	global_load_lds_dwordx4 v[2:3], off
	s_add_i32 m0, s72, 0x1c000
	v_lshl_add_u64 v[2:3], s[4:5], 0, v[0:1]
	global_load_lds_dwordx4 v[2:3], off
	v_lshl_add_u64 v[2:3], s[4:5], 0, v[184:185]
	s_add_i32 m0, s72, 0x1e000
	v_and_b32_e32 v186, 15, v11
	global_load_lds_dwordx4 v[2:3], off
	s_waitcnt vmcnt(8)
	s_barrier
	v_lshrrev_b32_e32 v2, 1, v11
	v_and_b32_e32 v2, 24, v2
	v_lshlrev_b32_e32 v3, 1, v2
	v_lshlrev_b32_e32 v4, 2, v11
	s_cmpk_lt_u32 s10, 0x100
	v_lshl_or_b32 v3, v186, 6, v3
	v_and_b32_e32 v4, 32, v4
	s_cselect_b64 s[24:25], -1, 0
	s_cmpk_gt_u32 s10, 0xff
	v_bitop3_b32 v208, v3, s7, v4 bitop3:0xde
	s_cselect_b64 s[28:29], -1, 0
	s_lshl_b32 s7, s11, 10
	s_lshl_b32 s10, s33, 8
	v_bitop3_b32 v5, v3, s6, v4 bitop3:0xde
	s_add_i32 s6, 0, 0x20000
	s_or_b32 s30, s10, s7
	s_add_i32 s7, s30, s6
	v_lshlrev_b32_e32 v3, 7, v186
	v_lshlrev_b32_e32 v4, 2, v2
	s_cmp_gt_i32 s11, 0
	v_add3_u32 v209, s7, v3, v4
	v_add_u32_e32 v3, s6, v4
	s_cselect_b64 s[26:27], -1, 0
	s_cmp_eq_u32 s11, 3
	v_cmp_lt_u32_e64 s[4:5], 13, v186
	v_cmp_lt_u32_e64 s[8:9], 1, v186
	v_add_u32_e32 v4, s30, v3
	s_cselect_b64 s[30:31], -1, 0
	s_or_b64 s[28:29], s[28:29], s[8:9]
	s_and_b64 s[30:31], s[4:5], s[30:31]
	s_add_i32 s36, s11, 2
	s_cmp_gt_i32 s11, -2
	v_lshl_or_b32 v173, s11, 6, v186
	s_cselect_b64 s[34:35], -1, 0
	s_lshl_b32 s11, s36, 10
	s_or_b32 s10, s10, s11
	v_lshl_or_b32 v219, s33, 5, v2
	v_lshlrev_b32_e32 v2, 14, v14
	v_add_u32_e32 v3, s10, v3
	s_cmp_eq_u32 s36, 3
	v_and_b32_e32 v2, 0xffff8000, v2
	v_add_u32_e32 v215, 0xfffffc00, v3
	v_add_u32_e32 v216, 0xfffffc10, v3
	v_add_u32_e32 v217, 0xfffffc80, v3
	v_add_u32_e32 v218, 0xfffffc90, v3
	s_cselect_b64 s[10:11], -1, 0
	s_cmp_lg_u32 s36, 0
	v_lshl_add_u32 v2, v15, 11, v2
	v_and_b32_e32 v3, 1, v14
	s_cselect_b64 s[36:37], -1, 0
	v_lshl_or_b32 v2, v3, 6, v2
	s_or_b64 s[36:37], s[36:37], s[8:9]
	s_and_b64 s[38:39], s[4:5], s[10:11]
	s_ashr_i32 s82, s66, 31
	v_lshl_add_u32 v190, v16, 1, v2
	v_lshlrev_b32_e32 v2, 14, v10
	s_add_u32 s40, s16, 0x2c00
	v_and_b32_e32 v2, 0xffff8000, v2
	s_waitcnt vmcnt(6)
	s_addc_u32 s41, s17, 0
	v_lshl_add_u32 v2, v12, 11, v2
	v_and_b32_e32 v3, 1, v10
	s_add_u32 s42, s16, 0x5800
	v_lshl_or_b32 v2, v3, 6, v2
	v_add_u32_e32 v210, 0xfffff900, v209
	s_mov_b32 s79, 0
	v_cmp_eq_u32_e64 s[6:7], 0, v186
	v_add_u32_e32 v188, -12, v186
	v_mov_b32_e32 v187, v1
	v_add_u32_e32 v211, 0xfffffc00, v4
	v_add_u32_e32 v212, 0xfffffc10, v4
	v_add_u32_e32 v213, 0xfffffc80, v4
	v_add_u32_e32 v214, 0xfffffc90, v4
	v_mov_b32_e32 v189, v1
	s_addc_u32 s43, s17, 0
	v_mov_b32_e32 v191, v1
	v_lshl_add_u32 v192, v13, 1, v2
	v_mov_b32_e32 v193, v1
	v_add_u32_e32 v220, 0, v5
	s_barrier
	s_branch .LBB0_1304

; #define PG8_STAGE(bufoff, gbase, voff) do { _Pragma("unroll") for (int _i = 0; _i < 2; ++_i) \
;         __builtin_amdgcn_global_load_lds((const unsigned*)((const char*)(gbase) + (voff)[_i]), (PG8_LAS unsigned*)(lds + (bufoff) + ldsw + _i * 8192), 16, 0, 0); } while (0)
; #define PG8_WAIT_V(n) asm volatile("s_waitcnt vmcnt(" #n ")" ::: "memory")
; #define PG8_BAR __builtin_amdgcn_s_barrier()
; template <class Epi>
; __device__ __forceinline__ void gemm_phase(PG8_LAS unsigned char* lds, const Gemm g, const StaticOrder& S_, const Epi& E) {
;     ...
;     PG8_STAGE(PG8_SB(0, 0), cB, voffB); PG8_STAGE(PG8_SB(0, 1), cB + hstepB, voffB); PG8_STAGE(PG8_SA(0, 0), cA, voffA); PG8_STAGE(PG8_SA(0, 1), cA + hstepA, voffA);
;     if (wr == 1) PG8_BAR;
;     PG8_WAIT_V(2); PG8_BAR;
;     PG8_STAGE(PG8_SB(1, 0), cB + kstep, voffB); PG8_STAGE(PG8_SA(1, 0), cA + kstep, voffA); PG8_STAGE(PG8_SB(1, 1), cB + hstepB + kstep, voffB);
;     PG8_WAIT_V(6); PG8_BAR;
.LBB0_1461:
	v_lshrrev_b32_e32 v20, 1, v15
	v_and_b32_e32 v20, 24, v20
	s_sext_i32_i8 s39, s10
	s_add_u32 s10, s4, 0x4800000
	v_and_b32_e32 v19, 15, v15
	v_lshlrev_b32_e32 v21, 1, v20
	v_lshlrev_b32_e32 v15, 2, v15
	s_addc_u32 s11, s5, 0
	v_lshl_or_b32 v140, s12, 6, v19
	v_lshl_or_b32 v19, v19, 6, v21
	s_lshl_b32 s4, s12, 13
	v_and_b32_e32 v15, 32, v15
	v_bitop3_b32 v21, v19, s4, v15 bitop3:0xde
	s_lshl_b32 s4, s7, 5
	s_and_b32 s7, s4, 0x60
	s_add_i32 m0, s29, 0x18000
	v_lshl_add_u64 v[8:9], v[8:9], 0, s[86:87]
	s_lshl_b32 s4, s7, 7
	global_load_lds_dwordx4 v[8:9], off
	v_lshl_add_u64 v[6:7], v[6:7], 0, s[86:87]
	s_add_i32 m0, s29, 0x1a000
	s_add_i32 s35, s29, 0x8000
	s_add_i32 s36, s29, 0xa000
	v_bitop3_b32 v141, v19, s4, v15 bitop3:0xde
	global_load_lds_dwordx4 v[6:7], off
	v_lshl_add_u64 v[2:3], v[2:3], 0, s[86:87]
	s_mov_b32 m0, s35
	s_add_u32 s4, s2, 0xb0080
	global_load_lds_dwordx4 v[2:3], off
	v_lshl_add_u64 v[2:3], v[4:5], 0, s[86:87]
	s_mov_b32 m0, s36
	s_addc_u32 s5, s3, 0
	global_load_lds_dwordx4 v[2:3], off
	s_add_i32 m0, s29, 0x1c000
	v_lshl_add_u64 v[2:3], s[4:5], 0, v[0:1]
	global_load_lds_dwordx4 v[2:3], off
	v_lshl_add_u64 v[2:3], s[4:5], 0, v[134:135]
	s_add_i32 m0, s29, 0x1e000
	s_cmpk_lt_u32 s6, 0x100
	global_load_lds_dwordx4 v[2:3], off
	s_waitcnt vmcnt(8)
	s_barrier
	s_movk_i32 s6, 0xb00
	v_or_b32_e32 v142, s7, v20
	v_lshrrev_b32_e32 v3, 1, v14
	v_mul_lo_u32 v2, v17, s6
	s_mov_b32 s7, 0xb000
	v_mad_u64_u32 v[2:3], s[4:5], v3, s7, v[2:3]
	v_or_b32_e32 v2, v2, v16
	v_add_lshl_u32 v2, v2, v18, 1
	v_mov_b32_e32 v3, v1
	s_mov_b64 s[14:15], 0xb0080
	v_lshl_add_u64 v[136:137], v[2:3], 0, s[14:15]
	v_lshrrev_b32_e32 v3, 1, v10
	v_mul_lo_u32 v2, v12, s6
	v_mad_u64_u32 v[2:3], s[4:5], v3, s7, v[2:3]
	s_waitcnt vmcnt(6)
	v_or_b32_e32 v2, v2, v11
	v_add_lshl_u32 v2, v2, v13, 1
	v_mov_b32_e32 v3, v1
	s_cselect_b64 s[12:13], -1, 0
	v_lshl_add_u64 v[138:139], v[2:3], 0, s[14:15]
	s_mov_b32 s38, 0
	v_add_u32_e32 v143, 0, v21
	s_barrier
	s_branch .LBB0_1464
